# ssd pass-1 x/B/C rows prefetched 2 sub-chunks ahead; attn_a item epilogue with all 32 gate loads batched
# speedup vs baseline: 1.0229x; 1.0229x over previous
; __device__ __forceinline__ v4i16 tr16(const unsigned char* p) { return __builtin_amdgcn_ds_read_tr16_b64_v4i16((LDSAS v4i16*)p); }
; __device__ __forceinline__ bf16x8 cat8(v4i16 a, v4i16 b) { return (bf16x8){a[0], a[1], a[2], a[3], b[0], b[1], b[2], b[3]}; }
; template <int PASS>
; __device__ void ssd_item(const Params& p, int item, int l, unsigned char* smem) {
;     ...
;     unsigned soff[5];
; #pragma unroll
;     for (int i = 0; i < 5; ++i) { const int u = tid + 256 * i, lrow = u / 40, ci = u % 40;
;         const int scol = ci < 8 ? h * 64 + ci * 8 : (ci < 24 ? 512 + grp * 128 + (ci * 8 - 64) : 768 + grp * 128 + (ci * 8 - 192));
;         soff[i] = (unsigned)((lrow * 1024 + scol) * 2); }
;     for (int si = 0; si < NSUB; ++si) {
;         const int scn = dir ? (NSUB - 1 - si) : si;
;         const int t0 = seg * SEGLEN + scn * TSUB;
;         __syncthreads();
;         u32x4 raw[5];
; #pragma unroll
;         for (int i = 0; i < 5; ++i) raw[i] = *(const u32x4*)(xb_ + ((unsigned)(t0 * 2048) + soff[i]));
;     ...
;         {
;             const float dc = __expf(stot);
;             const unsigned char* xw = (const unsigned char*)Xws + (8 * kq + (idx >> 2)) * 144 + (16 * w + 4 * (idx & 3)) * 2;
;             const bf16x8 xwf = cat8(tr16(xw), tr16(xw + 4 * 144));
;             bf16x8 bfv[8];
; #pragma unroll
;             for (int nt = 0; nt < 8; ++nt) {
;                 const unsigned char* bt = (const unsigned char*)Bs + (8 * kq + (idx >> 2)) * 272 + (16 * nt + 4 * (idx & 3)) * 2;
;                 bfv[nt] = cat8(tr16(bt), tr16(bt + 4 * 272));
;             }
;             __builtin_amdgcn_sched_barrier(0);
; #pragma unroll
;             for (int nt = 0; nt < 8; ++nt) S[nt] = __builtin_amdgcn_mfma_f32_16x16x32_bf16(bfv[nt], xwf, S[nt] * dc, 0, 0, 0);
;             __builtin_amdgcn_sched_barrier(0);
.LBB0_733:
	s_andn2_saveexec_b64 s[46:47], s[50:51]
	v_add_u32_e32 v10, s22, v9
	s_or_b64 exec, exec, s[46:47]
	v_lshlrev_b32_e32 v11, 11, v57
	v_lshl_add_u32 v60, v7, 1, v11
	v_lshlrev_b32_e32 v7, 11, v56
	v_lshl_add_u32 v61, v5, 1, v7
	v_lshlrev_b32_e32 v5, 11, v55
	v_lshl_add_u32 v62, v3, 1, v5
	v_lshlrev_b32_e32 v3, 11, v53
	v_lshl_add_u32 v63, v2, 1, v3
	v_lshlrev_b32_e32 v2, 11, v58
	v_lshl_add_u32 v64, v10, 1, v2
	v_lshrrev_b32_e32 v2, 1, v52
	v_bfe_u32 v3, v52, 2, 2
	v_ashrrev_i32_e32 v59, 6, v52
	v_and_or_b32 v2, v2, 24, v3
	v_mul_u32_u24_e32 v3, 0x90, v2
	v_lshlrev_b32_e32 v7, 5, v59
	v_add3_u32 v3, v54, v3, v7
	v_cmp_lt_u32_e64 s[46:47], 23, v1
	v_mul_lo_u32 v7, v53, s0
	v_lshlrev_b32_e32 v1, 4, v1
	v_add3_u32 v66, v54, v7, v1
	v_mul_lo_u32 v7, v53, s3
	s_lshl_b64 s[22:23], s[48:49], 24
	v_add3_u32 v68, v54, v7, v1
	v_cmp_lt_u32_e64 s[48:49], 23, v0
	v_mul_lo_u32 v1, v55, s0
	v_lshlrev_b32_e32 v0, 4, v0
	v_add3_u32 v69, v54, v1, v0
	v_mul_lo_u32 v1, v55, s3
	v_add3_u32 v71, v54, v1, v0
	v_mul_lo_u32 v0, v56, s0
	v_lshlrev_b32_e32 v1, 4, v4
	v_add3_u32 v72, v54, v0, v1
	v_mul_lo_u32 v0, v56, s3
	v_add3_u32 v74, v54, v0, v1
	v_mul_lo_u32 v0, v57, s0
	v_lshlrev_b32_e32 v1, 4, v6
	v_add3_u32 v75, v54, v0, v1
	v_mul_lo_u32 v0, v57, s3
	v_lshlrev_b32_e32 v5, 3, v52
	v_add3_u32 v77, v54, v0, v1
	v_mul_lo_u32 v0, v58, s0
	v_lshlrev_b32_e32 v1, 1, v9
	s_add_u32 s64, s18, s22
	v_and_b32_e32 v5, 24, v5
	v_mad_u32_u24 v2, v2, s0, v54
	v_add3_u32 v78, v54, v0, v1
	v_mul_lo_u32 v0, v58, s3
	v_mov_b32_e32 v65, 0
	s_addc_u32 s65, s19, s23
	s_lshl_b32 s12, s12, 20
	v_add_u32_e32 v67, 0xffffff80, v66
	v_add_u32_e32 v70, 0xffffff80, v69
	v_cmp_lt_u32_e64 s[50:51], 23, v4
	v_add_u32_e32 v73, 0xffffff80, v72
	v_cmp_lt_u32_e64 s[52:53], 23, v6
	v_add_u32_e32 v76, 0xffffff80, v75
	v_cmp_lt_u32_e64 s[54:55], 23, v8
	v_add_u32_e32 v79, 0xffffff80, v78
	v_add3_u32 v80, v54, v0, v1
	s_mov_b32 s22, 0
	s_mov_b32 s23, 15
	v_add_u32_e32 v82, v3, v5
	v_add_u32_e32 v83, v2, v5
	v_mov_b32_e32 v0, 0
	v_mov_b32_e32 v1, v65
	v_mov_b32_e32 v2, v65
	v_mov_b32_e32 v3, v65
	v_mov_b32_e32 v4, 0
	v_mov_b32_e32 v5, v65
	v_mov_b32_e32 v6, v65
	v_mov_b32_e32 v7, v65
	v_mov_b32_e32 v8, 0
	v_mov_b32_e32 v9, v65
	v_mov_b32_e32 v10, v65
	v_mov_b32_e32 v11, v65
	v_mov_b32_e32 v16, 0
	v_mov_b32_e32 v17, v65
	v_mov_b32_e32 v18, v65
	v_mov_b32_e32 v19, v65
	v_mov_b32_e32 v12, 0
	v_mov_b32_e32 v13, v65
	v_mov_b32_e32 v14, v65
	v_mov_b32_e32 v15, v65
	v_mov_b32_e32 v20, 0
	v_mov_b32_e32 v21, v65
	v_mov_b32_e32 v22, v65
	v_mov_b32_e32 v23, v65
	v_mov_b32_e32 v24, 0
	v_mov_b32_e32 v25, v65
	v_mov_b32_e32 v26, v65
	v_mov_b32_e32 v27, v65
	v_mov_b32_e32 v28, 0
	v_mov_b32_e32 v29, v65
	v_mov_b32_e32 v30, v65
	v_mov_b32_e32 v31, v65
	s_and_b64 s[24:25], vcc, exec
	s_cselect_b32 s99, 0, 15
	s_cselect_b32 s100, 1, 14
	s_lshl_b32 s99, s99, 16
	s_add_i32 s99, s99, s12
	s_lshl_b32 s100, s100, 16
	s_add_i32 s100, s100, s12
	v_add_u32_e32 v146, s99, v63
	global_load_dwordx4 v[104:107], v146, s[64:65]
	v_add_u32_e32 v147, s99, v62
	global_load_dwordx4 v[108:111], v147, s[64:65]
	v_add_u32_e32 v146, s99, v61
	global_load_dwordx4 v[112:115], v146, s[64:65]
	v_add_u32_e32 v147, s99, v60
	global_load_dwordx4 v[116:119], v147, s[64:65]
	v_add_u32_e32 v146, s99, v64
	global_load_dwordx4 v[120:123], v146, s[64:65]
	v_add_u32_e32 v146, s100, v63
	global_load_dwordx4 v[124:127], v146, s[64:65]
	v_add_u32_e32 v147, s100, v62
	global_load_dwordx4 v[128:131], v147, s[64:65]
	v_add_u32_e32 v146, s100, v61
	global_load_dwordx4 v[132:135], v146, s[64:65]
	v_add_u32_e32 v147, s100, v60
	global_load_dwordx4 v[138:141], v147, s[64:65]
	v_add_u32_e32 v146, s100, v64
	global_load_dwordx4 v[142:145], v146, s[64:65]
	s_branch .LBB0_737
.LBB0_736:
	s_or_b64 exec, exec, s[66:67]
	s_waitcnt lgkmcnt(0)
	s_barrier
	ds_read_b64_tr_b16 v[32:33], v82 offset:22016
	ds_read_b64_tr_b16 v[34:35], v82 offset:22592
	ds_read_b64_tr_b16 v[36:37], v83
	ds_read_b64_tr_b16 v[40:41], v83 offset:32
	ds_read_b64_tr_b16 v[44:45], v83 offset:64
	ds_read_b64_tr_b16 v[48:49], v83 offset:96
	ds_read_b64_tr_b16 v[86:87], v83 offset:128
	ds_read_b64_tr_b16 v[90:91], v83 offset:160
	ds_read_b64_tr_b16 v[46:47], v83 offset:1152
	ds_read_b64_tr_b16 v[50:51], v83 offset:1184
	ds_read_b64_tr_b16 v[88:89], v83 offset:1216
	ds_read_b64_tr_b16 v[92:93], v83 offset:1248
	ds_read_b64_tr_b16 v[38:39], v83 offset:1088
	ds_read_b64_tr_b16 v[42:43], v83 offset:1120
	ds_read_b64_tr_b16 v[94:95], v83 offset:192
	ds_read_b64_tr_b16 v[98:99], v83 offset:224
	ds_read_b64_tr_b16 v[96:97], v83 offset:1280
	ds_read_b64_tr_b16 v[100:101], v83 offset:1312
	v_mul_f32_e32 v85, 0x3fb8aa3b, v84
	v_exp_f32_e32 v102, v85
	s_nop 0
	v_pk_mul_f32 v[2:3], v[2:3], v[102:103] op_sel_hi:[1,0]
	v_pk_mul_f32 v[0:1], v[0:1], v[102:103] op_sel_hi:[1,0]
	v_pk_mul_f32 v[6:7], v[6:7], v[102:103] op_sel_hi:[1,0]
	v_pk_mul_f32 v[4:5], v[4:5], v[102:103] op_sel_hi:[1,0]
	v_pk_mul_f32 v[10:11], v[10:11], v[102:103] op_sel_hi:[1,0]
	v_pk_mul_f32 v[8:9], v[8:9], v[102:103] op_sel_hi:[1,0]
	v_pk_mul_f32 v[18:19], v[18:19], v[102:103] op_sel_hi:[1,0]
	v_pk_mul_f32 v[16:17], v[16:17], v[102:103] op_sel_hi:[1,0]
	v_pk_mul_f32 v[14:15], v[14:15], v[102:103] op_sel_hi:[1,0]
	v_pk_mul_f32 v[12:13], v[12:13], v[102:103] op_sel_hi:[1,0]
	v_pk_mul_f32 v[22:23], v[22:23], v[102:103] op_sel_hi:[1,0]
	v_pk_mul_f32 v[20:21], v[20:21], v[102:103] op_sel_hi:[1,0]
	v_pk_mul_f32 v[26:27], v[26:27], v[102:103] op_sel_hi:[1,0]
	v_pk_mul_f32 v[24:25], v[24:25], v[102:103] op_sel_hi:[1,0]
	v_pk_mul_f32 v[30:31], v[30:31], v[102:103] op_sel_hi:[1,0]
	v_pk_mul_f32 v[28:29], v[28:29], v[102:103] op_sel_hi:[1,0]
	s_waitcnt lgkmcnt(5)
	v_mfma_f32_16x16x32_bf16 v[0:3], v[36:39], v[32:35], v[0:3]
	v_add_f32_e32 v65, v65, v84
	s_waitcnt lgkmcnt(4)
	v_mfma_f32_16x16x32_bf16 v[4:7], v[40:43], v[32:35], v[4:7]
	v_mfma_f32_16x16x32_bf16 v[8:11], v[44:47], v[32:35], v[8:11]
	v_mfma_f32_16x16x32_bf16 v[16:19], v[48:51], v[32:35], v[16:19]
	v_mfma_f32_16x16x32_bf16 v[12:15], v[86:89], v[32:35], v[12:15]
	v_mfma_f32_16x16x32_bf16 v[20:23], v[90:93], v[32:35], v[20:23]
	s_waitcnt lgkmcnt(1)
	v_mfma_f32_16x16x32_bf16 v[24:27], v[94:97], v[32:35], v[24:27]
	s_waitcnt lgkmcnt(0)
	v_mfma_f32_16x16x32_bf16 v[28:31], v[98:101], v[32:35], v[28:31]
	s_add_i32 s22, s22, 1
	s_add_i32 s23, s23, -1
	s_cmp_eq_u32 s22, 16
	s_cbranch_scc1 .LBB0_777
.LBB0_737:
	s_add_i32 s99, s22, 2
	s_sub_i32 s100, 15, s99
	s_and_b64 s[24:25], vcc, exec
	s_cselect_b32 s101, s99, s100
	s_cselect_b32 s24, s22, s23
	s_lshl_b32 s101, s101, 16
	s_add_i32 s101, s101, s12
	s_waitcnt lgkmcnt(0)
	s_barrier
	s_cmp_gt_u32 s22, 13
	s_cbranch_scc1 .Lssd1_tailwait
	s_waitcnt vmcnt(5)
	s_branch .Lssd1_w

; template <int PASS>
; __device__ void ssd_item(const Params& p, int item, int l, unsigned char* smem) {
;     ...
;         u32x4 raw[5];
; #pragma unroll
;         for (int i = 0; i < 5; ++i) raw[i] = *(const u32x4*)(xb_ + ((unsigned)(t0 * 2048) + soff[i]));
;         const float* s_dt = s_dta + scn * TSUB; const float* s_c = s_cA + scn * TSUB; const float* s_rs = s_rsA + scn * TSUB; const float* s_wl = s_wlA + scn * TSUB;
;         const float stot = s_totA[scn];
;         segtot += stot;
.Lssd1_w:
	s_bitcmp1_b32 s22, 0
	s_cbranch_scc1 .Lssd1_odd
	v_mov_b32_e32 v48, v104
	v_mov_b32_e32 v49, v105
	v_mov_b32_e32 v50, v106
	v_mov_b32_e32 v51, v107
	v_mov_b32_e32 v44, v108
	v_mov_b32_e32 v45, v109
	v_mov_b32_e32 v46, v110
	v_mov_b32_e32 v47, v111
	v_mov_b32_e32 v40, v112
	v_mov_b32_e32 v41, v113
	v_mov_b32_e32 v42, v114
	v_mov_b32_e32 v43, v115
	v_mov_b32_e32 v36, v116
	v_mov_b32_e32 v37, v117
	v_mov_b32_e32 v38, v118
	v_mov_b32_e32 v39, v119
	v_mov_b32_e32 v32, v120
	v_mov_b32_e32 v33, v121
	v_mov_b32_e32 v34, v122
	v_mov_b32_e32 v35, v123
	s_cmp_gt_u32 s22, 13
	s_cbranch_scc1 .Lssd1_join
	v_add_u32_e32 v146, s101, v63
	global_load_dwordx4 v[104:107], v146, s[64:65]
	v_add_u32_e32 v147, s101, v62
	global_load_dwordx4 v[108:111], v147, s[64:65]
	v_add_u32_e32 v146, s101, v61
	global_load_dwordx4 v[112:115], v146, s[64:65]
	v_add_u32_e32 v147, s101, v60
	global_load_dwordx4 v[116:119], v147, s[64:65]
	v_add_u32_e32 v146, s101, v64
	global_load_dwordx4 v[120:123], v146, s[64:65]
	s_branch .Lssd1_join
.Lssd1_odd:
	v_mov_b32_e32 v48, v124
	v_mov_b32_e32 v49, v125
	v_mov_b32_e32 v50, v126
	v_mov_b32_e32 v51, v127
	v_mov_b32_e32 v44, v128
	v_mov_b32_e32 v45, v129
	v_mov_b32_e32 v46, v130
	v_mov_b32_e32 v47, v131
	v_mov_b32_e32 v40, v132
	v_mov_b32_e32 v41, v133
	v_mov_b32_e32 v42, v134
	v_mov_b32_e32 v43, v135
	v_mov_b32_e32 v36, v138
	v_mov_b32_e32 v37, v139
	v_mov_b32_e32 v38, v140
	v_mov_b32_e32 v39, v141
	v_mov_b32_e32 v32, v142
	v_mov_b32_e32 v33, v143
	v_mov_b32_e32 v34, v144
	v_mov_b32_e32 v35, v145
	s_cmp_gt_u32 s22, 13
	s_cbranch_scc1 .Lssd1_join
	v_add_u32_e32 v146, s101, v63
	global_load_dwordx4 v[124:127], v146, s[64:65]
	v_add_u32_e32 v147, s101, v62
	global_load_dwordx4 v[128:131], v147, s[64:65]
	v_add_u32_e32 v146, s101, v61
	global_load_dwordx4 v[132:135], v146, s[64:65]
	v_add_u32_e32 v147, s101, v60
	global_load_dwordx4 v[138:141], v147, s[64:65]
	v_add_u32_e32 v146, s101, v64
	global_load_dwordx4 v[142:145], v146, s[64:65]
.Lssd1_join:
	v_lshl_add_u32 v85, s24, 7, v54
	s_mulk_i32 s24, 0xff84
	v_add_u32_e32 v84, s24, v85
	ds_read_b32 v84, v84 offset:54272
	s_and_saveexec_b64 s[24:25], s[36:37]
	s_xor_b64 s[66:67], exec, s[24:25]
	s_cbranch_execnz .LBB0_747
	s_andn2_saveexec_b64 s[66:67], s[66:67]
	s_cbranch_execnz .LBB0_752

; __device__ __forceinline__ unsigned pk2(float lo, float hi) { f32x2 v = {lo, hi}; bf16x2_t b = __builtin_convertvector(v, bf16x2_t); return __builtin_bit_cast(unsigned, b); }
; __device__ __forceinline__ float bflo(unsigned u) { return __uint_as_float(u << 16); }
; __device__ __forceinline__ float bfhi(unsigned u) { return __uint_as_float(u & 0xffff0000u); }
; template <int PASS>
; __device__ void ssd_item(const Params& p, int item, int l, unsigned char* smem) {
;     ...
;         for (int i = 0; i < 5; ++i) { const int u = tid + 256 * i, lrow = u / 40, ci = u % 40, lc = ci * 8; const u32x4 o = raw[i];
;             if (ci < 8) { *(u32x4*)(Xs + lrow * 72 + lc) = o; const float wl = s_wl[lrow];
;                 u32x4 o2; o2.x = pk2(bflo(o.x) * wl, bfhi(o.x) * wl); o2.y = pk2(bflo(o.y) * wl, bfhi(o.y) * wl); o2.z = pk2(bflo(o.z) * wl, bfhi(o.z) * wl); o2.w = pk2(bflo(o.w) * wl, bfhi(o.w) * wl);
;                 *(u32x4*)(Xws + lrow * 72 + lc) = o2; }
;             else if (ci < 24) *(u32x4*)(Bs + lrow * 136 + (lc - 64)) = o;
;             else *(u32x4*)(Cs + lrow * 136 + (lc - 192)) = o; }
.LBB0_747:
	s_and_saveexec_b64 s[24:25], s[46:47]
	s_xor_b64 s[88:89], exec, s[24:25]
	s_cbranch_execz .LBB0_749
	ds_write_b128 v66, v[48:51] offset:8320
.LBB0_749:
	s_andn2_saveexec_b64 s[88:89], s[88:89]
	s_cbranch_execz .LBB0_751
	ds_write_b128 v67, v[48:51]

; __device__ __forceinline__ unsigned pk2(float lo, float hi) { f32x2 v = {lo, hi}; bf16x2_t b = __builtin_convertvector(v, bf16x2_t); return __builtin_bit_cast(unsigned, b); }
; __device__ __forceinline__ float bflo(unsigned u) { return __uint_as_float(u << 16); }
; __device__ __forceinline__ float bfhi(unsigned u) { return __uint_as_float(u & 0xffff0000u); }
; template <int PASS>
; __device__ void ssd_item(const Params& p, int item, int l, unsigned char* smem) {
;     ...
;         for (int i = 0; i < 5; ++i) { const int u = tid + 256 * i, lrow = u / 40, ci = u % 40, lc = ci * 8; const u32x4 o = raw[i];
;             if (ci < 8) { *(u32x4*)(Xs + lrow * 72 + lc) = o; const float wl = s_wl[lrow];
;                 u32x4 o2; o2.x = pk2(bflo(o.x) * wl, bfhi(o.x) * wl); o2.y = pk2(bflo(o.y) * wl, bfhi(o.y) * wl); o2.z = pk2(bflo(o.z) * wl, bfhi(o.z) * wl); o2.w = pk2(bflo(o.w) * wl, bfhi(o.w) * wl);
;                 *(u32x4*)(Xws + lrow * 72 + lc) = o2; }
;             else if (ci < 24) *(u32x4*)(Bs + lrow * 136 + (lc - 64)) = o;
;             else *(u32x4*)(Cs + lrow * 136 + (lc - 192)) = o; }
.LBB0_752:
	ds_write_b128 v68, v[48:51] offset:17408
	v_lshl_add_u32 v86, v53, 2, v85
	ds_read_b32 v86, v86 offset:50688
	v_lshlrev_b32_e32 v88, 16, v48
	v_and_b32_e32 v89, 0xffff0000, v48
	s_waitcnt lgkmcnt(0)
	v_pk_mul_f32 v[88:89], v[86:87], v[88:89] op_sel_hi:[0,1]
	v_cvt_pk_bf16_f32 v48, v88, v89
	v_lshlrev_b32_e32 v88, 16, v49
	v_and_b32_e32 v89, 0xffff0000, v49
	v_pk_mul_f32 v[88:89], v[86:87], v[88:89] op_sel_hi:[0,1]
	v_cvt_pk_bf16_f32 v49, v88, v89
	v_lshlrev_b32_e32 v88, 16, v50
	v_and_b32_e32 v89, 0xffff0000, v50
	v_pk_mul_f32 v[88:89], v[86:87], v[88:89] op_sel_hi:[0,1]
	v_cvt_pk_bf16_f32 v50, v88, v89
	v_lshlrev_b32_e32 v88, 16, v51
	v_and_b32_e32 v89, 0xffff0000, v51
	v_pk_mul_f32 v[86:87], v[86:87], v[88:89] op_sel_hi:[0,1]
	v_cvt_pk_bf16_f32 v51, v86, v87
	ds_write_b128 v68, v[48:51] offset:22016
	s_or_b64 exec, exec, s[66:67]
	s_and_saveexec_b64 s[24:25], s[38:39]
	s_xor_b64 s[66:67], exec, s[24:25]
	s_cbranch_execz .LBB0_740
.LBB0_753:
	s_and_saveexec_b64 s[24:25], s[48:49]
	s_xor_b64 s[88:89], exec, s[24:25]
	s_cbranch_execz .LBB0_755
	ds_write_b128 v69, v[44:47] offset:8320
.LBB0_755:
	s_andn2_saveexec_b64 s[88:89], s[88:89]
	s_cbranch_execz .LBB0_757
	ds_write_b128 v70, v[44:47]

; __device__ __forceinline__ unsigned pk2(float lo, float hi) { f32x2 v = {lo, hi}; bf16x2_t b = __builtin_convertvector(v, bf16x2_t); return __builtin_bit_cast(unsigned, b); }
; __device__ __forceinline__ float bflo(unsigned u) { return __uint_as_float(u << 16); }
; __device__ __forceinline__ float bfhi(unsigned u) { return __uint_as_float(u & 0xffff0000u); }
; template <int PASS>
; __device__ void ssd_item(const Params& p, int item, int l, unsigned char* smem) {
;     ...
;         for (int i = 0; i < 5; ++i) { const int u = tid + 256 * i, lrow = u / 40, ci = u % 40, lc = ci * 8; const u32x4 o = raw[i];
;             if (ci < 8) { *(u32x4*)(Xs + lrow * 72 + lc) = o; const float wl = s_wl[lrow];
;                 u32x4 o2; o2.x = pk2(bflo(o.x) * wl, bfhi(o.x) * wl); o2.y = pk2(bflo(o.y) * wl, bfhi(o.y) * wl); o2.z = pk2(bflo(o.z) * wl, bfhi(o.z) * wl); o2.w = pk2(bflo(o.w) * wl, bfhi(o.w) * wl);
;                 *(u32x4*)(Xws + lrow * 72 + lc) = o2; }
;             else if (ci < 24) *(u32x4*)(Bs + lrow * 136 + (lc - 64)) = o;
;             else *(u32x4*)(Cs + lrow * 136 + (lc - 192)) = o; }
.LBB0_758:
	ds_write_b128 v71, v[44:47] offset:17408
	v_lshl_add_u32 v48, v55, 2, v85
	ds_read_b32 v48, v48 offset:50688
	v_lshlrev_b32_e32 v50, 16, v44
	v_and_b32_e32 v51, 0xffff0000, v44
	s_waitcnt lgkmcnt(0)
	v_pk_mul_f32 v[50:51], v[48:49], v[50:51] op_sel_hi:[0,1]
	v_cvt_pk_bf16_f32 v44, v50, v51
	v_lshlrev_b32_e32 v50, 16, v45
	v_and_b32_e32 v51, 0xffff0000, v45
	v_pk_mul_f32 v[50:51], v[48:49], v[50:51] op_sel_hi:[0,1]
	v_cvt_pk_bf16_f32 v45, v50, v51
	v_lshlrev_b32_e32 v50, 16, v46
	v_and_b32_e32 v51, 0xffff0000, v46
	v_pk_mul_f32 v[50:51], v[48:49], v[50:51] op_sel_hi:[0,1]
	v_cvt_pk_bf16_f32 v46, v50, v51
	v_lshlrev_b32_e32 v50, 16, v47
	v_and_b32_e32 v51, 0xffff0000, v47
	v_pk_mul_f32 v[48:49], v[48:49], v[50:51] op_sel_hi:[0,1]
	v_cvt_pk_bf16_f32 v47, v48, v49
	ds_write_b128 v71, v[44:47] offset:22016
	s_or_b64 exec, exec, s[66:67]
	s_and_saveexec_b64 s[24:25], s[40:41]
	s_xor_b64 s[66:67], exec, s[24:25]
	s_cbranch_execz .LBB0_742
.LBB0_759:
	s_and_saveexec_b64 s[24:25], s[50:51]
	s_xor_b64 s[88:89], exec, s[24:25]
	s_cbranch_execz .LBB0_761
	ds_write_b128 v72, v[40:43] offset:8320
.LBB0_761:
	s_andn2_saveexec_b64 s[88:89], s[88:89]
	s_cbranch_execz .LBB0_763
	ds_write_b128 v73, v[40:43]

; __device__ __forceinline__ unsigned pk2(float lo, float hi) { f32x2 v = {lo, hi}; bf16x2_t b = __builtin_convertvector(v, bf16x2_t); return __builtin_bit_cast(unsigned, b); }
; __device__ __forceinline__ float bflo(unsigned u) { return __uint_as_float(u << 16); }
; __device__ __forceinline__ float bfhi(unsigned u) { return __uint_as_float(u & 0xffff0000u); }
; template <int PASS>
; __device__ void ssd_item(const Params& p, int item, int l, unsigned char* smem) {
;     ...
;         for (int i = 0; i < 5; ++i) { const int u = tid + 256 * i, lrow = u / 40, ci = u % 40, lc = ci * 8; const u32x4 o = raw[i];
;             if (ci < 8) { *(u32x4*)(Xs + lrow * 72 + lc) = o; const float wl = s_wl[lrow];
;                 u32x4 o2; o2.x = pk2(bflo(o.x) * wl, bfhi(o.x) * wl); o2.y = pk2(bflo(o.y) * wl, bfhi(o.y) * wl); o2.z = pk2(bflo(o.z) * wl, bfhi(o.z) * wl); o2.w = pk2(bflo(o.w) * wl, bfhi(o.w) * wl);
;                 *(u32x4*)(Xws + lrow * 72 + lc) = o2; }
;             else if (ci < 24) *(u32x4*)(Bs + lrow * 136 + (lc - 64)) = o;
;             else *(u32x4*)(Cs + lrow * 136 + (lc - 192)) = o; }
.LBB0_764:
	ds_write_b128 v74, v[40:43] offset:17408
	v_lshl_add_u32 v44, v56, 2, v85
	ds_read_b32 v44, v44 offset:50688
	v_lshlrev_b32_e32 v46, 16, v40
	v_and_b32_e32 v47, 0xffff0000, v40
	s_waitcnt lgkmcnt(0)
	v_pk_mul_f32 v[46:47], v[44:45], v[46:47] op_sel_hi:[0,1]
	v_cvt_pk_bf16_f32 v40, v46, v47
	v_lshlrev_b32_e32 v46, 16, v41
	v_and_b32_e32 v47, 0xffff0000, v41
	v_pk_mul_f32 v[46:47], v[44:45], v[46:47] op_sel_hi:[0,1]
	v_cvt_pk_bf16_f32 v41, v46, v47
	v_lshlrev_b32_e32 v46, 16, v42
	v_and_b32_e32 v47, 0xffff0000, v42
	v_pk_mul_f32 v[46:47], v[44:45], v[46:47] op_sel_hi:[0,1]
	v_cvt_pk_bf16_f32 v42, v46, v47
	v_lshlrev_b32_e32 v46, 16, v43
	v_and_b32_e32 v47, 0xffff0000, v43
	v_pk_mul_f32 v[44:45], v[44:45], v[46:47] op_sel_hi:[0,1]
	v_cvt_pk_bf16_f32 v43, v44, v45
	ds_write_b128 v74, v[40:43] offset:22016
	s_or_b64 exec, exec, s[66:67]
	s_and_saveexec_b64 s[24:25], s[42:43]
	s_xor_b64 s[66:67], exec, s[24:25]
	s_cbranch_execz .LBB0_744
.LBB0_765:
	s_and_saveexec_b64 s[24:25], s[52:53]
	s_xor_b64 s[88:89], exec, s[24:25]
	s_cbranch_execz .LBB0_767
	ds_write_b128 v75, v[36:39] offset:8320
.LBB0_767:
	s_andn2_saveexec_b64 s[88:89], s[88:89]
	s_cbranch_execz .LBB0_769
	ds_write_b128 v76, v[36:39]

; __device__ __forceinline__ unsigned pk2(float lo, float hi) { f32x2 v = {lo, hi}; bf16x2_t b = __builtin_convertvector(v, bf16x2_t); return __builtin_bit_cast(unsigned, b); }
; __device__ __forceinline__ float bflo(unsigned u) { return __uint_as_float(u << 16); }
; __device__ __forceinline__ float bfhi(unsigned u) { return __uint_as_float(u & 0xffff0000u); }
; template <int PASS>
; __device__ void ssd_item(const Params& p, int item, int l, unsigned char* smem) {
;     ...
;         for (int i = 0; i < 5; ++i) { const int u = tid + 256 * i, lrow = u / 40, ci = u % 40, lc = ci * 8; const u32x4 o = raw[i];
;             if (ci < 8) { *(u32x4*)(Xs + lrow * 72 + lc) = o; const float wl = s_wl[lrow];
;                 u32x4 o2; o2.x = pk2(bflo(o.x) * wl, bfhi(o.x) * wl); o2.y = pk2(bflo(o.y) * wl, bfhi(o.y) * wl); o2.z = pk2(bflo(o.z) * wl, bfhi(o.z) * wl); o2.w = pk2(bflo(o.w) * wl, bfhi(o.w) * wl);
;                 *(u32x4*)(Xws + lrow * 72 + lc) = o2; }
;             else if (ci < 24) *(u32x4*)(Bs + lrow * 136 + (lc - 64)) = o;
;             else *(u32x4*)(Cs + lrow * 136 + (lc - 192)) = o; }
.LBB0_770:
	ds_write_b128 v77, v[36:39] offset:17408
	v_lshl_add_u32 v40, v57, 2, v85
	ds_read_b32 v40, v40 offset:50688
	v_lshlrev_b32_e32 v42, 16, v36
	v_and_b32_e32 v43, 0xffff0000, v36
	s_waitcnt lgkmcnt(0)
	v_pk_mul_f32 v[42:43], v[40:41], v[42:43] op_sel_hi:[0,1]
	v_cvt_pk_bf16_f32 v36, v42, v43
	v_lshlrev_b32_e32 v42, 16, v37
	v_and_b32_e32 v43, 0xffff0000, v37
	v_pk_mul_f32 v[42:43], v[40:41], v[42:43] op_sel_hi:[0,1]
	v_cvt_pk_bf16_f32 v37, v42, v43
	v_lshlrev_b32_e32 v42, 16, v38
	v_and_b32_e32 v43, 0xffff0000, v38
	v_pk_mul_f32 v[42:43], v[40:41], v[42:43] op_sel_hi:[0,1]
	v_cvt_pk_bf16_f32 v38, v42, v43
	v_lshlrev_b32_e32 v42, 16, v39
	v_and_b32_e32 v43, 0xffff0000, v39
	v_pk_mul_f32 v[40:41], v[40:41], v[42:43] op_sel_hi:[0,1]
	v_cvt_pk_bf16_f32 v39, v40, v41
	ds_write_b128 v77, v[36:39] offset:22016
	s_or_b64 exec, exec, s[66:67]
	s_and_saveexec_b64 s[24:25], s[44:45]
	s_xor_b64 s[66:67], exec, s[24:25]
	s_cbranch_execz .LBB0_746
.LBB0_771:
	s_and_saveexec_b64 s[24:25], s[54:55]
	s_xor_b64 s[88:89], exec, s[24:25]
	s_cbranch_execz .LBB0_773
	ds_write_b128 v78, v[32:35] offset:8320
.LBB0_773:
	s_andn2_saveexec_b64 s[88:89], s[88:89]
	s_cbranch_execz .LBB0_775
	ds_write_b128 v79, v[32:35]

; __device__ __forceinline__ unsigned pk2(float lo, float hi) { f32x2 v = {lo, hi}; bf16x2_t b = __builtin_convertvector(v, bf16x2_t); return __builtin_bit_cast(unsigned, b); }
; __device__ __forceinline__ float bflo(unsigned u) { return __uint_as_float(u << 16); }
; __device__ __forceinline__ float bfhi(unsigned u) { return __uint_as_float(u & 0xffff0000u); }
; template <int PASS>
; __device__ void ssd_item(const Params& p, int item, int l, unsigned char* smem) {
;     ...
;         for (int i = 0; i < 5; ++i) { const int u = tid + 256 * i, lrow = u / 40, ci = u % 40, lc = ci * 8; const u32x4 o = raw[i];
;             if (ci < 8) { *(u32x4*)(Xs + lrow * 72 + lc) = o; const float wl = s_wl[lrow];
;                 u32x4 o2; o2.x = pk2(bflo(o.x) * wl, bfhi(o.x) * wl); o2.y = pk2(bflo(o.y) * wl, bfhi(o.y) * wl); o2.z = pk2(bflo(o.z) * wl, bfhi(o.z) * wl); o2.w = pk2(bflo(o.w) * wl, bfhi(o.w) * wl);
;                 *(u32x4*)(Xws + lrow * 72 + lc) = o2; }
;             else if (ci < 24) *(u32x4*)(Bs + lrow * 136 + (lc - 64)) = o;
;             else *(u32x4*)(Cs + lrow * 136 + (lc - 192)) = o; }
.LBB0_776:
	ds_write_b128 v80, v[32:35] offset:17408
	v_lshl_add_u32 v36, v58, 2, v85
	ds_read_b32 v36, v36 offset:50688
	v_lshlrev_b32_e32 v38, 16, v32
	v_and_b32_e32 v39, 0xffff0000, v32
	s_waitcnt lgkmcnt(0)
	v_pk_mul_f32 v[38:39], v[36:37], v[38:39] op_sel_hi:[0,1]
	v_cvt_pk_bf16_f32 v32, v38, v39
	v_lshlrev_b32_e32 v38, 16, v33
	v_and_b32_e32 v39, 0xffff0000, v33
	v_pk_mul_f32 v[38:39], v[36:37], v[38:39] op_sel_hi:[0,1]
	v_cvt_pk_bf16_f32 v33, v38, v39
	v_lshlrev_b32_e32 v38, 16, v34
	v_and_b32_e32 v39, 0xffff0000, v34
	v_pk_mul_f32 v[38:39], v[36:37], v[38:39] op_sel_hi:[0,1]
	v_cvt_pk_bf16_f32 v34, v38, v39
	v_lshlrev_b32_e32 v38, 16, v35
	v_and_b32_e32 v39, 0xffff0000, v35
	v_pk_mul_f32 v[36:37], v[36:37], v[38:39] op_sel_hi:[0,1]
	v_cvt_pk_bf16_f32 v35, v36, v37
	ds_write_b128 v80, v[32:35] offset:22016
	s_branch .LBB0_736

; __device__ __forceinline__ unsigned pk2(float lo, float hi) { f32x2 v = {lo, hi}; bf16x2_t b = __builtin_convertvector(v, bf16x2_t); return __builtin_bit_cast(unsigned, b); }
; __device__ __forceinline__ float bf2f(unsigned short b) { return __uint_as_float(((unsigned)b) << 16); }
; __device__ __forceinline__ int crow(int r, int hi) { return (r & 3) + 8 * (r >> 2) + 4 * hi; }
; __device__ void attn_a_item(const Params& p, int item, int l, unsigned char* smem) {
;     ...
;     float lacc = (la4.x + la4.y) + (la4.z + la4.w);
;     lacc += __shfl_xor(lacc, 32);
;     if (hi == 0) lq[r32] = lacc;
;     asm volatile("s_waitcnt lgkmcnt(0)" ::: "memory");
; #pragma unroll
;     for (int rr = 0; rr < 16; ++rr) {
;         const int q = crow(rr, hi); const float inv = 1.f / lq[q];
;         const size_t off = (tokq + q) * 512 + hq * 64 + r32;
;         const float g0 = bf2f(GA[off]), g1 = bf2f(GA[off + 32]);
;         QA[off] = (bf16_t)(pk2(o0[rr] * inv * g0, 0.f) & 0xffffu);
;         QA[off + 32] = (bf16_t)(pk2(o1[rr] * inv * g1, 0.f) & 0xffffu);
;     }
.LBB0_844:
	s_or_b64 exec, exec, s[44:45]
	s_waitcnt lgkmcnt(0)
	v_lshl_add_u32 v112, v152, 4, s12
	ds_read_b128 v[32:35], v112 offset:34816
	ds_read_b128 v[36:39], v112 offset:34848
	ds_read_b128 v[40:43], v112 offset:34880
	ds_read_b128 v[44:47], v112 offset:34912
	v_or_b32_e32 v110, s18, v153
	v_lshlrev_b32_e32 v110, 1, v110
	v_lshl_or_b32 v111, v152, 2, s9
	v_lshl_or_b32 v98, v111, 10, v110
	v_or_b32_e32 v102, 8, v111
	v_lshl_or_b32 v99, v102, 10, v110
	v_or_b32_e32 v102, 16, v111
	v_lshl_or_b32 v100, v102, 10, v110
	v_or_b32_e32 v102, 24, v111
	v_lshl_or_b32 v101, v102, 10, v110
	global_load_ushort v64, v98, s[40:41]
	global_load_ushort v82, v98, s[40:41] offset:64
	global_load_ushort v65, v98, s[40:41] offset:1024
	global_load_ushort v83, v98, s[40:41] offset:1088
	global_load_ushort v66, v98, s[40:41] offset:2048
	global_load_ushort v84, v98, s[40:41] offset:2112
	global_load_ushort v67, v98, s[40:41] offset:3072
	global_load_ushort v85, v98, s[40:41] offset:3136
	global_load_ushort v68, v99, s[40:41]
	global_load_ushort v86, v99, s[40:41] offset:64
	global_load_ushort v69, v99, s[40:41] offset:1024
	global_load_ushort v87, v99, s[40:41] offset:1088
	global_load_ushort v70, v99, s[40:41] offset:2048
	global_load_ushort v88, v99, s[40:41] offset:2112
	global_load_ushort v71, v99, s[40:41] offset:3072
	global_load_ushort v89, v99, s[40:41] offset:3136
	global_load_ushort v72, v100, s[40:41]
	global_load_ushort v90, v100, s[40:41] offset:64
	global_load_ushort v73, v100, s[40:41] offset:1024
	global_load_ushort v91, v100, s[40:41] offset:1088
	global_load_ushort v74, v100, s[40:41] offset:2048
	global_load_ushort v92, v100, s[40:41] offset:2112
	global_load_ushort v75, v100, s[40:41] offset:3072
	global_load_ushort v93, v100, s[40:41] offset:3136
	global_load_ushort v76, v101, s[40:41]
	global_load_ushort v94, v101, s[40:41] offset:64
	global_load_ushort v77, v101, s[40:41] offset:1024
	global_load_ushort v95, v101, s[40:41] offset:1088
	global_load_ushort v78, v101, s[40:41] offset:2048
	global_load_ushort v96, v101, s[40:41] offset:2112
	global_load_ushort v79, v101, s[40:41] offset:3072
	global_load_ushort v97, v101, s[40:41] offset:3136
	s_waitcnt lgkmcnt(0)
	v_div_scale_f32 v102, s[100:101], v32, v32, 1.0
	v_rcp_f32_e32 v103, v102
	s_nop 0
	v_fma_f32 v104, -v102, v103, 1.0
	v_fmac_f32_e32 v103, v104, v103
	v_div_scale_f32 v104, vcc, 1.0, v32, 1.0
	v_mul_f32_e32 v105, v104, v103
	v_fma_f32 v106, -v102, v105, v104
	v_fmac_f32_e32 v105, v106, v103
	v_fma_f32 v102, -v102, v105, v104
	v_div_fmas_f32 v102, v102, v103, v105
	v_div_fixup_f32 v48, v102, v32, 1.0
	v_div_scale_f32 v102, s[100:101], v33, v33, 1.0
	v_rcp_f32_e32 v103, v102
	s_nop 0
	v_fma_f32 v104, -v102, v103, 1.0
	v_fmac_f32_e32 v103, v104, v103
	v_div_scale_f32 v104, vcc, 1.0, v33, 1.0
	v_mul_f32_e32 v105, v104, v103
	v_fma_f32 v106, -v102, v105, v104
	v_fmac_f32_e32 v105, v106, v103
	v_fma_f32 v102, -v102, v105, v104
	v_div_fmas_f32 v102, v102, v103, v105
	v_div_fixup_f32 v49, v102, v33, 1.0
	v_div_scale_f32 v102, s[100:101], v34, v34, 1.0
	v_rcp_f32_e32 v103, v102
	s_nop 0
	v_fma_f32 v104, -v102, v103, 1.0
	v_fmac_f32_e32 v103, v104, v103
	v_div_scale_f32 v104, vcc, 1.0, v34, 1.0
	v_mul_f32_e32 v105, v104, v103
	v_fma_f32 v106, -v102, v105, v104
	v_fmac_f32_e32 v105, v106, v103
	v_fma_f32 v102, -v102, v105, v104
	v_div_fmas_f32 v102, v102, v103, v105
	v_div_fixup_f32 v50, v102, v34, 1.0
	v_div_scale_f32 v102, s[100:101], v35, v35, 1.0
	v_rcp_f32_e32 v103, v102
	s_nop 0
	v_fma_f32 v104, -v102, v103, 1.0
	v_fmac_f32_e32 v103, v104, v103
	v_div_scale_f32 v104, vcc, 1.0, v35, 1.0
	v_mul_f32_e32 v105, v104, v103
	v_fma_f32 v106, -v102, v105, v104
	v_fmac_f32_e32 v105, v106, v103
	v_fma_f32 v102, -v102, v105, v104
	v_div_fmas_f32 v102, v102, v103, v105
	v_div_fixup_f32 v51, v102, v35, 1.0
	v_div_scale_f32 v102, s[100:101], v36, v36, 1.0
	v_rcp_f32_e32 v103, v102
	s_nop 0
	v_fma_f32 v104, -v102, v103, 1.0
	v_fmac_f32_e32 v103, v104, v103
	v_div_scale_f32 v104, vcc, 1.0, v36, 1.0
	v_mul_f32_e32 v105, v104, v103
	v_fma_f32 v106, -v102, v105, v104
	v_fmac_f32_e32 v105, v106, v103
	v_fma_f32 v102, -v102, v105, v104
	v_div_fmas_f32 v102, v102, v103, v105
	v_div_fixup_f32 v52, v102, v36, 1.0
	v_div_scale_f32 v102, s[100:101], v37, v37, 1.0
	v_rcp_f32_e32 v103, v102
	s_nop 0
	v_fma_f32 v104, -v102, v103, 1.0
	v_fmac_f32_e32 v103, v104, v103
	v_div_scale_f32 v104, vcc, 1.0, v37, 1.0
	v_mul_f32_e32 v105, v104, v103
	v_fma_f32 v106, -v102, v105, v104
	v_fmac_f32_e32 v105, v106, v103
	v_fma_f32 v102, -v102, v105, v104
	v_div_fmas_f32 v102, v102, v103, v105
	v_div_fixup_f32 v53, v102, v37, 1.0
	v_div_scale_f32 v102, s[100:101], v38, v38, 1.0
	v_rcp_f32_e32 v103, v102
	s_nop 0
	v_fma_f32 v104, -v102, v103, 1.0
	v_fmac_f32_e32 v103, v104, v103
	v_div_scale_f32 v104, vcc, 1.0, v38, 1.0
	v_mul_f32_e32 v105, v104, v103
	v_fma_f32 v106, -v102, v105, v104
	v_fmac_f32_e32 v105, v106, v103
	v_fma_f32 v102, -v102, v105, v104
	v_div_fmas_f32 v102, v102, v103, v105
	v_div_fixup_f32 v54, v102, v38, 1.0
	v_div_scale_f32 v102, s[100:101], v39, v39, 1.0
	v_rcp_f32_e32 v103, v102
	s_nop 0
	v_fma_f32 v104, -v102, v103, 1.0
	v_fmac_f32_e32 v103, v104, v103
	v_div_scale_f32 v104, vcc, 1.0, v39, 1.0
	v_mul_f32_e32 v105, v104, v103
	v_fma_f32 v106, -v102, v105, v104
	v_fmac_f32_e32 v105, v106, v103
	v_fma_f32 v102, -v102, v105, v104
	v_div_fmas_f32 v102, v102, v103, v105
	v_div_fixup_f32 v55, v102, v39, 1.0
	v_div_scale_f32 v102, s[100:101], v40, v40, 1.0
	v_rcp_f32_e32 v103, v102
	s_nop 0
	v_fma_f32 v104, -v102, v103, 1.0
	v_fmac_f32_e32 v103, v104, v103
	v_div_scale_f32 v104, vcc, 1.0, v40, 1.0
; __device__ __forceinline__ unsigned pk2(float lo, float hi) { f32x2 v = {lo, hi}; bf16x2_t b = __builtin_convertvector(v, bf16x2_t); return __builtin_bit_cast(unsigned, b); }
; __device__ __forceinline__ float bf2f(unsigned short b) { return __uint_as_float(((unsigned)b) << 16); }
; __device__ __forceinline__ int crow(int r, int hi) { return (r & 3) + 8 * (r >> 2) + 4 * hi; }
; __device__ void attn_a_item(const Params& p, int item, int l, unsigned char* smem) {
;     ...
; #pragma unroll
;     for (int rr = 0; rr < 16; ++rr) {
;         const int q = crow(rr, hi); const float inv = 1.f / lq[q];
;         const size_t off = (tokq + q) * 512 + hq * 64 + r32;
;         const float g0 = bf2f(GA[off]), g1 = bf2f(GA[off + 32]);
;         QA[off] = (bf16_t)(pk2(o0[rr] * inv * g0, 0.f) & 0xffffu);
;         QA[off + 32] = (bf16_t)(pk2(o1[rr] * inv * g1, 0.f) & 0xffffu);
;     }
	v_mul_f32_e32 v105, v104, v103
	v_fma_f32 v106, -v102, v105, v104
	v_fmac_f32_e32 v105, v106, v103
	v_fma_f32 v102, -v102, v105, v104
	v_div_fmas_f32 v102, v102, v103, v105
	v_div_fixup_f32 v56, v102, v40, 1.0
	v_div_scale_f32 v102, s[100:101], v41, v41, 1.0
	v_rcp_f32_e32 v103, v102
	s_nop 0
	v_fma_f32 v104, -v102, v103, 1.0
	v_fmac_f32_e32 v103, v104, v103
	v_div_scale_f32 v104, vcc, 1.0, v41, 1.0
	v_mul_f32_e32 v105, v104, v103
	v_fma_f32 v106, -v102, v105, v104
	v_fmac_f32_e32 v105, v106, v103
	v_fma_f32 v102, -v102, v105, v104
	v_div_fmas_f32 v102, v102, v103, v105
	v_div_fixup_f32 v57, v102, v41, 1.0
	v_div_scale_f32 v102, s[100:101], v42, v42, 1.0
	v_rcp_f32_e32 v103, v102
	s_nop 0
	v_fma_f32 v104, -v102, v103, 1.0
	v_fmac_f32_e32 v103, v104, v103
	v_div_scale_f32 v104, vcc, 1.0, v42, 1.0
	v_mul_f32_e32 v105, v104, v103
	v_fma_f32 v106, -v102, v105, v104
	v_fmac_f32_e32 v105, v106, v103
	v_fma_f32 v102, -v102, v105, v104
	v_div_fmas_f32 v102, v102, v103, v105
	v_div_fixup_f32 v58, v102, v42, 1.0
	v_div_scale_f32 v102, s[100:101], v43, v43, 1.0
	v_rcp_f32_e32 v103, v102
	s_nop 0
	v_fma_f32 v104, -v102, v103, 1.0
	v_fmac_f32_e32 v103, v104, v103
	v_div_scale_f32 v104, vcc, 1.0, v43, 1.0
	v_mul_f32_e32 v105, v104, v103
	v_fma_f32 v106, -v102, v105, v104
	v_fmac_f32_e32 v105, v106, v103
	v_fma_f32 v102, -v102, v105, v104
	v_div_fmas_f32 v102, v102, v103, v105
	v_div_fixup_f32 v59, v102, v43, 1.0
	v_div_scale_f32 v102, s[100:101], v44, v44, 1.0
	v_rcp_f32_e32 v103, v102
	s_nop 0
	v_fma_f32 v104, -v102, v103, 1.0
	v_fmac_f32_e32 v103, v104, v103
	v_div_scale_f32 v104, vcc, 1.0, v44, 1.0
	v_mul_f32_e32 v105, v104, v103
	v_fma_f32 v106, -v102, v105, v104
	v_fmac_f32_e32 v105, v106, v103
	v_fma_f32 v102, -v102, v105, v104
	v_div_fmas_f32 v102, v102, v103, v105
	v_div_fixup_f32 v60, v102, v44, 1.0
	v_div_scale_f32 v102, s[100:101], v45, v45, 1.0
	v_rcp_f32_e32 v103, v102
	s_nop 0
	v_fma_f32 v104, -v102, v103, 1.0
	v_fmac_f32_e32 v103, v104, v103
	v_div_scale_f32 v104, vcc, 1.0, v45, 1.0
	v_mul_f32_e32 v105, v104, v103
	v_fma_f32 v106, -v102, v105, v104
	v_fmac_f32_e32 v105, v106, v103
	v_fma_f32 v102, -v102, v105, v104
	v_div_fmas_f32 v102, v102, v103, v105
	v_div_fixup_f32 v61, v102, v45, 1.0
	v_div_scale_f32 v102, s[100:101], v46, v46, 1.0
	v_rcp_f32_e32 v103, v102
	s_nop 0
	v_fma_f32 v104, -v102, v103, 1.0
	v_fmac_f32_e32 v103, v104, v103
	v_div_scale_f32 v104, vcc, 1.0, v46, 1.0
	v_mul_f32_e32 v105, v104, v103
	v_fma_f32 v106, -v102, v105, v104
	v_fmac_f32_e32 v105, v106, v103
	v_fma_f32 v102, -v102, v105, v104
	v_div_fmas_f32 v102, v102, v103, v105
	v_div_fixup_f32 v62, v102, v46, 1.0
	v_div_scale_f32 v102, s[100:101], v47, v47, 1.0
	v_rcp_f32_e32 v103, v102
	s_nop 0
	v_fma_f32 v104, -v102, v103, 1.0
	v_fmac_f32_e32 v103, v104, v103
	v_div_scale_f32 v104, vcc, 1.0, v47, 1.0
	v_mul_f32_e32 v105, v104, v103
	v_fma_f32 v106, -v102, v105, v104
	v_fmac_f32_e32 v105, v106, v103
	v_fma_f32 v102, -v102, v105, v104
	v_div_fmas_f32 v102, v102, v103, v105
	v_div_fixup_f32 v63, v102, v47, 1.0
	s_waitcnt vmcnt(0)
	v_lshlrev_b32_e32 v64, 16, v64
	v_mul_f32_e32 v0, v0, v48
	v_mul_f32_e32 v0, v0, v64
	v_cvt_pk_bf16_f32 v0, v0, s0
	global_store_short v98, v0, s[36:37]
	v_lshlrev_b32_e32 v82, 16, v82
	v_mul_f32_e32 v16, v16, v48
	v_mul_f32_e32 v16, v16, v82
	v_cvt_pk_bf16_f32 v16, v16, s0
	global_store_short v98, v16, s[36:37] offset:64
	v_lshlrev_b32_e32 v65, 16, v65
	v_mul_f32_e32 v1, v1, v49
	v_mul_f32_e32 v1, v1, v65
	v_cvt_pk_bf16_f32 v1, v1, s0
	global_store_short v98, v1, s[36:37] offset:1024
	v_lshlrev_b32_e32 v83, 16, v83
	v_mul_f32_e32 v17, v17, v49
	v_mul_f32_e32 v17, v17, v83
	v_cvt_pk_bf16_f32 v17, v17, s0
	global_store_short v98, v17, s[36:37] offset:1088
	v_lshlrev_b32_e32 v66, 16, v66
	v_mul_f32_e32 v2, v2, v50
	v_mul_f32_e32 v2, v2, v66
	v_cvt_pk_bf16_f32 v2, v2, s0
	global_store_short v98, v2, s[36:37] offset:2048
	v_lshlrev_b32_e32 v84, 16, v84
	v_mul_f32_e32 v18, v18, v50
	v_mul_f32_e32 v18, v18, v84
	v_cvt_pk_bf16_f32 v18, v18, s0
	global_store_short v98, v18, s[36:37] offset:2112
	v_lshlrev_b32_e32 v67, 16, v67
	v_mul_f32_e32 v3, v3, v51
	v_mul_f32_e32 v3, v3, v67
	v_cvt_pk_bf16_f32 v3, v3, s0
	global_store_short v98, v3, s[36:37] offset:3072
	v_lshlrev_b32_e32 v85, 16, v85
	v_mul_f32_e32 v19, v19, v51
	v_mul_f32_e32 v19, v19, v85
	v_cvt_pk_bf16_f32 v19, v19, s0
	global_store_short v98, v19, s[36:37] offset:3136
	v_lshlrev_b32_e32 v68, 16, v68
	v_mul_f32_e32 v4, v4, v52
	v_mul_f32_e32 v4, v4, v68
	v_cvt_pk_bf16_f32 v4, v4, s0
	global_store_short v99, v4, s[36:37]
	v_lshlrev_b32_e32 v86, 16, v86
	v_mul_f32_e32 v20, v20, v52
	v_mul_f32_e32 v20, v20, v86
	v_cvt_pk_bf16_f32 v20, v20, s0
	global_store_short v99, v20, s[36:37] offset:64
	v_lshlrev_b32_e32 v69, 16, v69
	v_mul_f32_e32 v5, v5, v53
	v_mul_f32_e32 v5, v5, v69
	v_cvt_pk_bf16_f32 v5, v5, s0
	global_store_short v99, v5, s[36:37] offset:1024
	v_lshlrev_b32_e32 v87, 16, v87
	v_mul_f32_e32 v21, v21, v53
	v_mul_f32_e32 v21, v21, v87
	v_cvt_pk_bf16_f32 v21, v21, s0
	global_store_short v99, v21, s[36:37] offset:1088
	v_lshlrev_b32_e32 v70, 16, v70
	v_mul_f32_e32 v6, v6, v54
	v_mul_f32_e32 v6, v6, v70
	v_cvt_pk_bf16_f32 v6, v6, s0
	global_store_short v99, v6, s[36:37] offset:2048
	v_lshlrev_b32_e32 v88, 16, v88
	v_mul_f32_e32 v22, v22, v54
	v_mul_f32_e32 v22, v22, v88
	v_cvt_pk_bf16_f32 v22, v22, s0
	global_store_short v99, v22, s[36:37] offset:2112
	v_lshlrev_b32_e32 v71, 16, v71
	v_mul_f32_e32 v7, v7, v55
	v_mul_f32_e32 v7, v7, v71
	v_cvt_pk_bf16_f32 v7, v7, s0
	global_store_short v99, v7, s[36:37] offset:3072
	v_lshlrev_b32_e32 v89, 16, v89
	v_mul_f32_e32 v23, v23, v55
; __device__ __forceinline__ unsigned pk2(float lo, float hi) { f32x2 v = {lo, hi}; bf16x2_t b = __builtin_convertvector(v, bf16x2_t); return __builtin_bit_cast(unsigned, b); }
; __device__ __forceinline__ float bf2f(unsigned short b) { return __uint_as_float(((unsigned)b) << 16); }
; __device__ __forceinline__ int crow(int r, int hi) { return (r & 3) + 8 * (r >> 2) + 4 * hi; }
; __device__ void attn_a_item(const Params& p, int item, int l, unsigned char* smem) {
;     ...
; #pragma unroll
;     for (int rr = 0; rr < 16; ++rr) {
;         const int q = crow(rr, hi); const float inv = 1.f / lq[q];
;         const size_t off = (tokq + q) * 512 + hq * 64 + r32;
;         const float g0 = bf2f(GA[off]), g1 = bf2f(GA[off + 32]);
;         QA[off] = (bf16_t)(pk2(o0[rr] * inv * g0, 0.f) & 0xffffu);
;         QA[off + 32] = (bf16_t)(pk2(o1[rr] * inv * g1, 0.f) & 0xffffu);
;     }
; __global__ void __launch_bounds__(512, 2) hybrid_fwd(Params p) {
;     ...
; #pragma unroll 1
;               for (int it = blockIdx.x; it < 512; it += gridDim.x) attn_a_item(q, it, l, smem);
	v_mul_f32_e32 v23, v23, v89
	v_cvt_pk_bf16_f32 v23, v23, s0
	global_store_short v99, v23, s[36:37] offset:3136
	v_lshlrev_b32_e32 v72, 16, v72
	v_mul_f32_e32 v8, v8, v56
	v_mul_f32_e32 v8, v8, v72
	v_cvt_pk_bf16_f32 v8, v8, s0
	global_store_short v100, v8, s[36:37]
	v_lshlrev_b32_e32 v90, 16, v90
	v_mul_f32_e32 v24, v24, v56
	v_mul_f32_e32 v24, v24, v90
	v_cvt_pk_bf16_f32 v24, v24, s0
	global_store_short v100, v24, s[36:37] offset:64
	v_lshlrev_b32_e32 v73, 16, v73
	v_mul_f32_e32 v9, v9, v57
	v_mul_f32_e32 v9, v9, v73
	v_cvt_pk_bf16_f32 v9, v9, s0
	global_store_short v100, v9, s[36:37] offset:1024
	v_lshlrev_b32_e32 v91, 16, v91
	v_mul_f32_e32 v25, v25, v57
	v_mul_f32_e32 v25, v25, v91
	v_cvt_pk_bf16_f32 v25, v25, s0
	global_store_short v100, v25, s[36:37] offset:1088
	v_lshlrev_b32_e32 v74, 16, v74
	v_mul_f32_e32 v10, v10, v58
	v_mul_f32_e32 v10, v10, v74
	v_cvt_pk_bf16_f32 v10, v10, s0
	global_store_short v100, v10, s[36:37] offset:2048
	v_lshlrev_b32_e32 v92, 16, v92
	v_mul_f32_e32 v26, v26, v58
	v_mul_f32_e32 v26, v26, v92
	v_cvt_pk_bf16_f32 v26, v26, s0
	global_store_short v100, v26, s[36:37] offset:2112
	v_lshlrev_b32_e32 v75, 16, v75
	v_mul_f32_e32 v11, v11, v59
	v_mul_f32_e32 v11, v11, v75
	v_cvt_pk_bf16_f32 v11, v11, s0
	global_store_short v100, v11, s[36:37] offset:3072
	v_lshlrev_b32_e32 v93, 16, v93
	v_mul_f32_e32 v27, v27, v59
	v_mul_f32_e32 v27, v27, v93
	v_cvt_pk_bf16_f32 v27, v27, s0
	global_store_short v100, v27, s[36:37] offset:3136
	v_lshlrev_b32_e32 v76, 16, v76
	v_mul_f32_e32 v12, v12, v60
	v_mul_f32_e32 v12, v12, v76
	v_cvt_pk_bf16_f32 v12, v12, s0
	global_store_short v101, v12, s[36:37]
	v_lshlrev_b32_e32 v94, 16, v94
	v_mul_f32_e32 v28, v28, v60
	v_mul_f32_e32 v28, v28, v94
	v_cvt_pk_bf16_f32 v28, v28, s0
	global_store_short v101, v28, s[36:37] offset:64
	v_lshlrev_b32_e32 v77, 16, v77
	v_mul_f32_e32 v13, v13, v61
	v_mul_f32_e32 v13, v13, v77
	v_cvt_pk_bf16_f32 v13, v13, s0
	global_store_short v101, v13, s[36:37] offset:1024
	v_lshlrev_b32_e32 v95, 16, v95
	v_mul_f32_e32 v29, v29, v61
	v_mul_f32_e32 v29, v29, v95
	v_cvt_pk_bf16_f32 v29, v29, s0
	global_store_short v101, v29, s[36:37] offset:1088
	v_lshlrev_b32_e32 v78, 16, v78
	v_mul_f32_e32 v14, v14, v62
	v_mul_f32_e32 v14, v14, v78
	v_cvt_pk_bf16_f32 v14, v14, s0
	global_store_short v101, v14, s[36:37] offset:2048
	v_lshlrev_b32_e32 v96, 16, v96
	v_mul_f32_e32 v30, v30, v62
	v_mul_f32_e32 v30, v30, v96
	v_cvt_pk_bf16_f32 v30, v30, s0
	global_store_short v101, v30, s[36:37] offset:2112
	v_lshlrev_b32_e32 v79, 16, v79
	v_mul_f32_e32 v15, v15, v63
	v_mul_f32_e32 v15, v15, v79
	v_cvt_pk_bf16_f32 v15, v15, s0
	global_store_short v101, v15, s[36:37] offset:3072
	v_lshlrev_b32_e32 v97, 16, v97
	v_mul_f32_e32 v31, v31, v63
	v_mul_f32_e32 v31, v31, v97
	v_cvt_pk_bf16_f32 v31, v31, s0
	global_store_short v101, v31, s[36:37] offset:3136
	s_add_i32 s49, s49, s8
	s_cmpk_gt_i32 s49, 0x1ff
	s_cbranch_scc1 .LBB0_854
; #define ATA_LOAD(RK, RV, t) do { const size_t tb = (size_t)(t) * 64 * 128; RK[0] = *(const u32x4*)(Kb + tb + goff0); RV[0] = *(const u32x4*)(Vb + tb + goff0); } while (0)
; #define ATA_STORE(RK, RV, st) do { unsigned char* sb_ = smem + (st) * ATA_STAGE; *(u32x4*)(sb_ + ko0) = RK[0]; *(u32x4*)(sb_ + vo0) = RV[0]; } while (0)
; __device__ void attn_a_item(const Params& p, int item, int l, unsigned char* smem) {
;     ...
;     const int tid = tid_, lane = tid & 63, w = __builtin_amdgcn_readfirstlane(tid >> 6), r32 = lane & 31, hi = lane >> 5;
;     const int b = item >> 8, r = item & 255, kvh = r >> 7, qblk = (r >> 2) & 31, hq = kvh * 4 + (r & 3);
;     float* lq = (float*)(smem + ATA_LQ) + w * 32;
;     bf16_t* QA = (bf16_t*)(p.ws + WS_QA);
;     const bf16_t* GA = (const bf16_t*)(p.ws + WS_GA);
;     const size_t tokq = (size_t)b * SEQ + qblk * 256 + w * 32;
;     bf16x8 qr[4];
; #pragma unroll
;     for (int ds = 0; ds < 4; ++ds) qr[ds] = *(const bf16x8*)(QA + (tokq + r32) * 512 + hq * 64 + ds * 16 + hi * 8);
;     const bf16_t* Kb = (const bf16_t*)(p.ws + WS_KA) + (size_t)b * SEQ * 128 + kvh * 64;
;     const bf16_t* Vb = (const bf16_t*)(p.ws + WS_VA) + (size_t)b * SEQ * 128 + kvh * 64;
;     const float nshift = -((const float*)(p.ws + WS_BND))[l];
;     f32x16 o0, o1;
; #pragma unroll
;     for (int i = 0; i < 16; ++i) { o0[i] = 0.f; o1[i] = 0.f; }
;     f32x4 la4 = (f32x4){0.f, 0.f, 0.f, 0.f};
;     constexpr int NT = SEQ / 64;
;     const int row0 = tid >> 3, ch0 = tid & 7;
;     const size_t goff0 = (size_t)row0 * 128 + ch0 * 8;
;     const int ko0 = row0 * 144 + ch0 * 16;
;     const int vo0 = 9216 + (ch0 >> 2) * 4096 + row0 * 64 + (ch0 & 3) * 16;
;     u32x4 rkA[1], rvA[1], rkB[1], rvB[1];
;     ...
;     __syncthreads();
;     ATA_LOAD(rkA, rvA, 0); ATA_LOAD(rkB, rvB, 1);
;     ATA_STORE(rkA, rvA, 0);
;     ATA_LOAD(rkA, rvA, 2);
;     __syncthreads();
.LBB0_845:
	v_mov_b32_e32 v11, v210
	s_ashr_i32 s20, s49, 8
	v_readfirstlane_b32 s9, v11
	s_ashr_i32 s17, s9, 1
	s_ashr_i32 s21, s20, 31
	s_lshl_b32 s22, s49, 6
	s_bfe_u32 s12, s49, 0x10007
	s_andn2_b32 s17, s17, 31
	s_lshl_b64 s[18:19], s[20:21], 13
	s_and_b32 s9, s22, 0x1f00
	s_lshl_b32 s24, s12, 7
	s_ashr_i32 s16, s17, 31
	s_or_b32 s9, s18, s9
	s_add_u32 s9, s9, s17
	v_and_b32_e32 v153, 31, v11
	s_addc_u32 s16, s19, s16
	v_or_b32_e32 v0, s9, v153
	v_mov_b32_e32 v1, s16
	s_lshl_b32 s12, s12, 8
	s_and_b32 s18, s22, 0xc0
	v_lshlrev_b64 v[0:1], 10, v[0:1]
	s_or_b32 s18, s12, s18
	v_lshl_add_u64 v[0:1], s[36:37], 0, v[0:1]
	s_lshl_b32 s12, s18, 1
	s_lshl_b64 s[44:45], s[20:21], 21
	v_lshl_add_u64 v[0:1], v[0:1], 0, s[12:13]
	s_add_u32 s12, s11, s44
	s_addc_u32 s19, s46, s45
	v_bfe_u32 v152, v11, 5, 1
	s_add_u32 s20, s47, s44
	v_ashrrev_i32_e32 v8, 3, v11
	v_lshlrev_b32_e32 v80, 4, v152
	s_addc_u32 s21, s48, s45
	v_ashrrev_i32_e32 v9, 31, v8
	v_lshlrev_b32_e32 v23, 4, v11
	v_lshl_add_u64 v[0:1], v[0:1], 0, v[80:81]
	s_add_u32 s20, s20, s24
	v_and_b32_e32 v10, 0x70, v23
	v_lshlrev_b64 v[12:13], 8, v[8:9]
	global_load_dwordx4 v[82:85], v[0:1], off
	global_load_dwordx4 v[86:89], v[0:1], off offset:32
	global_load_dwordx4 v[90:93], v[0:1], off offset:64
	global_load_dwordx4 v[94:97], v[0:1], off offset:96
	s_addc_u32 s21, s21, 0
	v_or_b32_e32 v0, v12, v10
	v_mov_b32_e32 v1, v13
	v_lshl_add_u64 v[14:15], s[20:21], 0, v[0:1]
	s_add_u32 s22, s12, s24
	v_add_co_u32_e32 v18, vcc, s34, v14
	s_addc_u32 s23, s19, 0
	s_nop 0
	v_addc_co_u32_e32 v19, vcc, 0, v15, vcc
	s_mov_b32 s19, 0x8000
	global_load_dword v22, v81, s[38:39]
	s_barrier
	v_lshl_add_u64 v[16:17], s[22:23], 0, v[0:1]
	global_load_dwordx4 v[0:3], v[14:15], off
	global_load_dwordx4 v[4:7], v[16:17], off
	v_add_co_u32_e32 v14, vcc, s19, v14
	v_lshlrev_b32_e32 v9, 10, v11
	s_nop 0
	v_addc_co_u32_e32 v15, vcc, 0, v15, vcc
	v_add_co_u32_e32 v20, vcc, s34, v16
	v_and_b32_e32 v9, 0x1000, v9
	s_nop 0
	v_addc_co_u32_e32 v21, vcc, 0, v17, vcc
	v_add_co_u32_e32 v16, vcc, s19, v16
	v_lshlrev_b32_e32 v24, 1, v11
	s_nop 0
	v_addc_co_u32_e32 v17, vcc, 0, v17, vcc
	global_load_dwordx4 v[102:105], v[18:19], off
	global_load_dwordx4 v[110:113], v[20:21], off
	global_load_dwordx4 v[98:101], v[14:15], off
	global_load_dwordx4 v[106:109], v[16:17], off
	v_and_b32_e32 v16, 48, v23
	v_mad_u64_u32 v[14:15], s[20:21], v8, s3, v[10:11]
	v_lshl_or_b32 v8, v8, 6, v16
	v_lshlrev_b32_e32 v25, 3, v11
	v_add_u32_e32 v155, 0, v14
	v_add_u32_e32 v8, v8, v9
	v_and_b32_e32 v18, 32, v24
	v_add_u32_e32 v156, 0, v8
	v_mul_u32_u24_e32 v17, 0x48, v153
	v_lshlrev_b32_e32 v15, 1, v17
	v_mov_b32_e32 v116, 0
	s_mov_b32 s12, 0
	v_and_b32_e32 v154, 63, v11
	v_add3_u32 v80, 0, v15, v80
	v_mov_b32_e32 v117, v116
	v_mov_b32_e32 v118, v116
	v_mov_b32_e32 v119, v116
	v_mov_b32_e32 v8, v116
	v_mov_b32_e32 v9, v116
	v_mov_b32_e32 v14, v116
	v_mov_b32_e32 v15, v116
	v_mov_b32_e32 v16, v116
	v_mov_b32_e32 v17, v116
	s_waitcnt vmcnt(5)
	ds_write_b128 v155, v[0:3]
	s_waitcnt vmcnt(4)
	ds_write_b128 v156, v[4:7] offset:9216
	v_and_b32_e32 v0, 24, v25
	v_add3_u32 v2, 0, v18, v0
	v_lshrrev_b32_e32 v0, 3, v11
	v_bfe_u32 v1, v11, 2, 2
	v_and_or_b32 v0, v0, 4, v1
	v_lshlrev_b32_e32 v3, 6, v0
	v_lshl_add_u64 v[0:1], s[44:45], 0, v[12:13]
	v_xor_b32_e32 v32, 0x80000000, v22
	v_or3_b32 v0, v0, s24, v10
	v_mov_b32_e32 v33, v32
	v_mov_b32_e32 v34, v32
	v_mov_b32_e32 v35, v32
	v_mov_b32_e32 v36, v32
	v_mov_b32_e32 v37, v32
	v_mov_b32_e32 v38, v32
	v_mov_b32_e32 v39, v32
	v_mov_b32_e32 v40, v32
	v_mov_b32_e32 v41, v32
	v_mov_b32_e32 v42, v32
	v_mov_b32_e32 v43, v32
	v_mov_b32_e32 v44, v32
	v_mov_b32_e32 v45, v32
	v_mov_b32_e32 v46, v32
	v_mov_b32_e32 v47, v32
	v_lshl_add_u64 v[114:115], s[42:43], 0, v[0:1]
	v_add_u32_e32 v157, v2, v3
	v_mov_b32_e32 v0, v116
	v_mov_b32_e32 v1, v116
	v_mov_b32_e32 v2, v116
	v_mov_b32_e32 v3, v116
	v_mov_b32_e32 v4, v116
	v_mov_b32_e32 v5, v116
	v_mov_b32_e32 v6, v116
	v_mov_b32_e32 v7, v116
	v_mov_b32_e32 v10, v116
	v_mov_b32_e32 v11, v116
	v_mov_b32_e32 v12, v116
	v_mov_b32_e32 v13, v116
	v_mov_b32_e32 v18, v116
	v_mov_b32_e32 v19, v116
	v_mov_b32_e32 v20, v116
	v_mov_b32_e32 v21, v116
	v_mov_b32_e32 v22, v116
	v_mov_b32_e32 v23, v116
	v_mov_b32_e32 v24, v116
	v_mov_b32_e32 v25, v116
	v_mov_b32_e32 v26, v116
	v_mov_b32_e32 v27, v116
	v_mov_b32_e32 v28, v116
	v_mov_b32_e32 v29, v116
	v_mov_b32_e32 v30, v116
	v_mov_b32_e32 v31, v116
	s_waitcnt lgkmcnt(0)
	s_barrier
	s_branch .LBB0_847

; #define LDSAS __attribute__((address_space(3)))
; #define VBLK vblk_()
; __device__ __forceinline__ unsigned char* lds_half(unsigned char* smem) { int h_ = threadIdx.x >> 8; asm volatile("" : "+v"(h_)); return smem + h_ * HALF_LDS; }
; __global__ void __launch_bounds__(512, 2) hybrid_fwd(Params p) {
;     cg::grid_group grid = cg::this_grid();
;     extern __shared__ __attribute__((aligned(16))) unsigned char smem[];
;     volatile LDSAS unsigned* bst = (volatile LDSAS unsigned*)(smem + LDS_TOTAL - 16);
;     if (threadIdx.x < 4) bst[threadIdx.x] = 0u;
;     __syncthreads();
;     const XcdBarrier xbar = xcd_barrier_post((unsigned*)(p.ws + WS_BAR), bst);
;     { const Params q = launder(p); phase0(q, lds_half(smem)); }
;     grid.sync();
; #pragma unroll 1
;     for (int l = 0; l < DEPTH; ++l) {
; #pragma unroll 1
;         for (int hb = 0; hb < 2; ++hb) {
;             { const Params q = launder(p); norm_phase(q, l, hb, (l == 0) ? q.x : q.out); }
;             xcd_barrier(xbar);
;             { const Params q = launder(p); gemm1_phase(q, l, hb, smem); }
;             xcd_barrier(xbar);
;             { const Params q = launder(p); conv_phase(q, l); }
;             xcd_barrier(xbar);
;             { const Params q = launder(p); unsigned char* smh = lds_half(smem);
; #pragma unroll 1
;               for (int it = VBLK; it < 512; it += VGRID) ssd_item<1>(q, it, l, smh);
; #pragma unroll 1
;               for (int it = blockIdx.x; it < 768; it += gridDim.x) attn_b_item(q, it, l, smem); }
;             xcd_barrier(xbar);
;             { const Params q = launder(p);
; #pragma unroll 1
;               for (int it = blockIdx.x; it < 512; it += gridDim.x) attn_a_item(q, it, l, smem);
;               unsigned char* smh = lds_half(smem);
; #pragma unroll 1
;               for (int it = VBLK; it < 512; it += VGRID) ssd_item<3>(q, it, l, smh); }
;             xcd_barrier(xbar);
;             { const Params q = launder(p); post2_phase(q); }
;             xcd_barrier(xbar);
;             { const Params q = launder(p); merge_phase(q, l, smem); }
;             xcd_barrier(xbar);
;             { const Params q = launder(p); out_phase(q, l, hb, (l == 0) ? q.x : q.out, smem); }
;         }
;     }
; }
	.amdhsa_kernel _Z10hybrid_fwd6Params
		.amdhsa_group_segment_fixed_size 0
		.amdhsa_private_segment_fixed_size 0
		.amdhsa_kernarg_size 448
		.amdhsa_user_sgpr_count 2
		.amdhsa_user_sgpr_dispatch_ptr 0
		.amdhsa_user_sgpr_queue_ptr 0
		.amdhsa_user_sgpr_kernarg_segment_ptr 1
		.amdhsa_user_sgpr_dispatch_id 0
		.amdhsa_user_sgpr_kernarg_preload_length 0
		.amdhsa_user_sgpr_kernarg_preload_offset 0
		.amdhsa_user_sgpr_private_segment_size 0
		.amdhsa_uses_dynamic_stack 0
		.amdhsa_enable_private_segment 0
		.amdhsa_system_sgpr_workgroup_id_x 1
		.amdhsa_system_sgpr_workgroup_id_y 0
		.amdhsa_system_sgpr_workgroup_id_z 0
		.amdhsa_system_sgpr_workgroup_info 0
		.amdhsa_system_vgpr_workitem_id 2
		.amdhsa_next_free_vgpr 256
		.amdhsa_next_free_sgpr 102
		.amdhsa_accum_offset 256
		.amdhsa_reserve_vcc 1
		.amdhsa_float_round_mode_32 0
		.amdhsa_float_round_mode_16_64 0
		.amdhsa_float_denorm_mode_32 3
		.amdhsa_float_denorm_mode_16_64 3
		.amdhsa_dx10_clamp 1
		.amdhsa_ieee_mode 1
		.amdhsa_fp16_overflow 0
		.amdhsa_tg_split 0
		.amdhsa_exception_fp_ieee_invalid_op 0
		.amdhsa_exception_fp_denorm_src 0
		.amdhsa_exception_fp_ieee_div_zero 0
		.amdhsa_exception_fp_ieee_overflow 0
		.amdhsa_exception_fp_ieee_underflow 0
		.amdhsa_exception_fp_ieee_inexact 0
		.amdhsa_exception_int_div_zero 0
	.end_amdhsa_kernel

; #define LDSAS __attribute__((address_space(3)))
; #define VBLK vblk_()
; __device__ __forceinline__ unsigned char* lds_half(unsigned char* smem) { int h_ = threadIdx.x >> 8; asm volatile("" : "+v"(h_)); return smem + h_ * HALF_LDS; }
; __global__ void __launch_bounds__(512, 2) hybrid_fwd(Params p) {
;     cg::grid_group grid = cg::this_grid();
;     extern __shared__ __attribute__((aligned(16))) unsigned char smem[];
;     volatile LDSAS unsigned* bst = (volatile LDSAS unsigned*)(smem + LDS_TOTAL - 16);
;     if (threadIdx.x < 4) bst[threadIdx.x] = 0u;
;     __syncthreads();
;     const XcdBarrier xbar = xcd_barrier_post((unsigned*)(p.ws + WS_BAR), bst);
;     { const Params q = launder(p); phase0(q, lds_half(smem)); }
;     grid.sync();
; #pragma unroll 1
;     for (int l = 0; l < DEPTH; ++l) {
; #pragma unroll 1
;         for (int hb = 0; hb < 2; ++hb) {
;             { const Params q = launder(p); norm_phase(q, l, hb, (l == 0) ? q.x : q.out); }
;             xcd_barrier(xbar);
;             { const Params q = launder(p); gemm1_phase(q, l, hb, smem); }
;             xcd_barrier(xbar);
;             { const Params q = launder(p); conv_phase(q, l); }
;             xcd_barrier(xbar);
;             { const Params q = launder(p); unsigned char* smh = lds_half(smem);
; #pragma unroll 1
;               for (int it = VBLK; it < 512; it += VGRID) ssd_item<1>(q, it, l, smh);
; #pragma unroll 1
;               for (int it = blockIdx.x; it < 768; it += gridDim.x) attn_b_item(q, it, l, smem); }
;             xcd_barrier(xbar);
;             { const Params q = launder(p);
; #pragma unroll 1
;               for (int it = blockIdx.x; it < 512; it += gridDim.x) attn_a_item(q, it, l, smem);
;               unsigned char* smh = lds_half(smem);
; #pragma unroll 1
;               for (int it = VBLK; it < 512; it += VGRID) ssd_item<3>(q, it, l, smh); }
;             xcd_barrier(xbar);
;             { const Params q = launder(p); post2_phase(q); }
;             xcd_barrier(xbar);
;             { const Params q = launder(p); merge_phase(q, l, smem); }
;             xcd_barrier(xbar);
;             { const Params q = launder(p); out_phase(q, l, hb, (l == 0) ? q.x : q.out, smem); }
;         }
;     }
; }
amdhsa.kernels:
  - .agpr_count:     0
    .args:
      - .offset:         0
        .size:           192
        .value_kind:     by_value
      - .offset:         192
        .size:           4
        .value_kind:     hidden_block_count_x
      - .offset:         196
        .size:           4
        .value_kind:     hidden_block_count_y
      - .offset:         200
        .size:           4
        .value_kind:     hidden_block_count_z
      - .offset:         204
        .size:           2
        .value_kind:     hidden_group_size_x
      - .offset:         206
        .size:           2
        .value_kind:     hidden_group_size_y
      - .offset:         208
        .size:           2
        .value_kind:     hidden_group_size_z
      - .offset:         210
        .size:           2
        .value_kind:     hidden_remainder_x
      - .offset:         212
        .size:           2
        .value_kind:     hidden_remainder_y
      - .offset:         214
        .size:           2
        .value_kind:     hidden_remainder_z
      - .offset:         232
        .size:           8
        .value_kind:     hidden_global_offset_x
      - .offset:         240
        .size:           8
        .value_kind:     hidden_global_offset_y
      - .offset:         248
        .size:           8
        .value_kind:     hidden_global_offset_z
      - .offset:         256
        .size:           2
        .value_kind:     hidden_grid_dims
      - .offset:         280
        .size:           8
        .value_kind:     hidden_multigrid_sync_arg
      - .offset:         312
        .size:           4
        .value_kind:     hidden_dynamic_lds_size
    .group_segment_fixed_size: 0
    .kernarg_segment_align: 8
    .kernarg_segment_size: 448
    .language:       OpenCL C
    .language_version:
      - 2
      - 0
    .max_flat_workgroup_size: 512
    .name:           _Z10hybrid_fwd6Params
    .private_segment_fixed_size: 0
    .sgpr_count:     108
    .sgpr_spill_count: 186
    .symbol:         _Z10hybrid_fwd6Params.kd
    .uniform_work_group_size: 1
    .uses_dynamic_stack: false
    .vgpr_count:     256
    .vgpr_spill_count: 0
    .wavefront_size: 64
